# conversion engine: weight loads now issued at the end of load segment 1 (after its DMAs) with conditional vmcnt at W1-W3, giving them a 3-phase landing window
# speedup vs baseline: 1.0014x; 1.0014x over previous
; #define GAS __attribute__((address_space(1)))
; __device__ __forceinline__ void conv_load(const ConvItem& it, int lane, f32x4 (&v)[4]) {
;     const int lk = lane >> 3, ln = (lane & 7) * 4;
; #pragma unroll
;     for (int i = 0; i < 4; ++i) v[i] = __builtin_nontemporal_load((const GAS f32x4*)(it.W + (size_t)(it.k0 + 8 * i + lk) * it.N + it.n0 + ln));
; }
.Leng_mat:
	s_and_b32 s101, s85, 0xffff
	s_mul_i32 s97, s93, 0x158000
	s_add_u32 s98, s98, s97
	s_addc_u32 s99, s99, 0
	s_lshl_b32 s97, s101, 7
	s_add_u32 s98, s98, s97
	s_addc_u32 s99, s99, 0
	s_lshr_b32 s97, s101, 2
	s_lshl_b32 s97, s97, 8
	s_add_i32 s100, s100, s97
	s_and_b32 s97, s101, 3
	s_lshl_b32 s97, s97, 5
	s_add_i32 s100, s100, s97
	s_lshl_b32 s100, s100, 13
	s_lshl_b32 s97, s93, 6
	s_add_i32 s100, s100, s97
	v_readlane_b32 s97, v244, 6
	v_readlane_b32 s101, v244, 7
	s_nop 3
	s_add_u32 s100, s97, s100
	s_addc_u32 s101, s101, 0
	s_mov_b32 s97, 8
	s_branch .Leng_done

; #define GAS __attribute__((address_space(1)))
; __device__ __forceinline__ void conv_load(const ConvItem& it, int lane, f32x4 (&v)[4]) {
;     const int lk = lane >> 3, ln = (lane & 7) * 4;
; #pragma unroll
;     for (int i = 0; i < 4; ++i) v[i] = __builtin_nontemporal_load((const GAS f32x4*)(it.W + (size_t)(it.k0 + 8 * i + lk) * it.N + it.n0 + ln));
; }
.Leng_Bm:
	s_nop 3
	s_add_u32 s100, s100, s97
	s_addc_u32 s101, s101, 0
	s_lshr_b32 s97, s93, 7
	s_and_b32 s93, s93, 0x7f
	s_lshl_b32 s97, s97, 6
	s_add_u32 s100, s100, s97
	s_addc_u32 s101, s101, 0
	s_lshl_b32 s97, s97, 13
	s_add_u32 s98, s98, s97
	s_addc_u32 s99, s99, 0
	s_lshl_b32 s97, s93, 7
	s_add_u32 s98, s98, s97
	s_addc_u32 s99, s99, 0
	s_lshl_b32 s97, s93, 18
	s_add_u32 s100, s100, s97
	s_addc_u32 s101, s101, 0
	s_or_b32 s100, s100, 1
	s_mov_b32 s97, 4
	s_branch .Leng_done

; #define PG8_STAGE(bufoff, gbase, voff) do { _Pragma("unroll") for (int _i = 0; _i < 2; ++_i) \
;         __builtin_amdgcn_global_load_lds((const unsigned*)((const char*)(gbase) + (voff)[_i]), (PG8_LAS unsigned*)(lds + (bufoff) + ldsw + _i * 8192), 16, 0, 0); } while (0)
; #define PG8_LDA(dst, b, h) do { _Pragma("unroll") for (int m = 0; m < 4; ++m) _Pragma("unroll") for (int k = 0; k < 2; ++k) dst[m][k] = *(const PG8_LAS bf16x8*)(lds + PG8_SA(b, h) + aoff + m * 2048 + k * 1024); } while (0)
; #define PG8_LDB(dst, b, h) do { _Pragma("unroll") for (int n = 0; n < 2; ++n) _Pragma("unroll") for (int k = 0; k < 2; ++k) dst[n][k] = *(const PG8_LAS bf16x8*)(lds + PG8_SB(b, h) + boff + n * 2048 + k * 1024); } while (0)
; #define PG8_SCHED __builtin_amdgcn_sched_barrier(0)
; #define GAS __attribute__((address_space(1)))
; template <class Epi, class Sched, bool ALIGN_EPI = false, bool SP2 = false>
; __device__ __forceinline__ void gemm_phase(PG8_LAS unsigned char* lds, const Gemm g, const Sched& S, const Epi& E) {
;     ...
;             PG8_LDB(B0, 0, 0); PG8_LDB(B1, 0, 1); PG8_SCHED; PG8_LDA(At, 0, 0); PG8_STAGE(PG8_SA(1, 1), a1 + hstepA, voffA);
; __device__ __forceinline__ void conv_load(const ConvItem& it, int lane, f32x4 (&v)[4]) {
;     const int lk = lane >> 3, ln = (lane & 7) * 4;
; #pragma unroll
;     for (int i = 0; i < 4; ++i) v[i] = __builtin_nontemporal_load((const GAS f32x4*)(it.W + (size_t)(it.k0 + 8 * i + lk) * it.N + it.n0 + ln));
; }
.Leng_done:
	ds_read_b128 v[130:133], v167
	ds_read_b128 v[134:137], v167 offset:1024
	ds_read_b128 v[156:159], v167 offset:2048
	ds_read_b128 v[172:175], v167 offset:3072
	ds_read_b128 v[176:179], v168
	ds_read_b128 v[180:183], v168 offset:1024
	ds_read_b128 v[184:187], v168 offset:2048
	ds_read_b128 v[188:191], v168 offset:3072
	s_add_u32 s8, s6, 0xfff00080
	s_addc_u32 s9, s7, -1
	s_cmp_eq_u32 s45, 60
	s_cselect_b32 s37, s1, s9
	s_cselect_b32 s36, s14, s8
	s_cselect_b32 s9, s25, s44
	s_cselect_b32 s8, s27, s33
	v_lshl_add_u64 v[160:161], s[6:7], 0, v[148:149]
	s_add_i32 m0, s55, 0xc000
	ds_read_b128 v[192:195], v169
	ds_read_b128 v[196:199], v169 offset:1024
	ds_read_b128 v[200:203], v169 offset:2048
	ds_read_b128 v[204:207], v169 offset:3072
	ds_read_b128 v[208:211], v169 offset:4096
	ds_read_b128 v[212:215], v169 offset:5120
	ds_read_b128 v[216:219], v169 offset:6144
	ds_read_b128 v[220:223], v169 offset:7168
	global_load_lds_dwordx4 v[160:161], off
	v_lshl_add_u64 v[160:161], s[6:7], 0, v[150:151]
	s_add_i32 m0, s55, 0xe000
	s_nop 0
	global_load_lds_dwordx4 v[160:161], off
	s_cmp_lt_u32 s97, 4
	s_cbranch_scc1 .Leng_ld_done
	v_lshrrev_b32_e32 v254, 3, v1
	v_and_b32_e32 v255, 7, v1
	s_cmp_eq_u32 s97, 8
	s_cbranch_scc0 .Leng_ldB
	v_mul_u32_u24_e32 v254, 0xac00, v254
	v_lshl_add_u32 v254, v255, 4, v254
	global_load_dwordx4 v[232:235], v254, s[98:99] nt
	s_add_u32 s98, s98, 0x56000
	s_addc_u32 s99, s99, 0
	global_load_dwordx4 v[236:239], v254, s[98:99] nt
	s_add_u32 s98, s98, 0x56000
	s_addc_u32 s99, s99, 0
	global_load_dwordx4 v[240:243], v254, s[98:99] nt
	s_add_u32 s98, s98, 0x56000
	s_addc_u32 s99, s99, 0
	global_load_dwordx4 v[246:249], v254, s[98:99] nt
	v_readlane_b32 s98, v245, 4
	v_readlane_b32 s99, v245, 5
	v_lshrrev_b32_e32 v255, 3, v1
	v_lshlrev_b32_e32 v255, 2, v255
	s_lshl_b32 s93, s93, 7
	s_nop 1
	s_add_u32 s98, s98, s93
	s_addc_u32 s99, s99, 0
	global_load_dword v250, v255, s[98:99]
	global_load_dword v251, v255, s[98:99] offset:32
	global_load_dword v252, v255, s[98:99] offset:64
	global_load_dword v253, v255, s[98:99] offset:96
	s_branch .Leng_ld_done
.Leng_ldB:
	v_lshlrev_b32_e32 v254, 14, v254
	v_lshl_add_u32 v254, v255, 4, v254
	s_nop 0
	global_load_dwordx4 v[232:235], v254, s[98:99] nt
	s_add_u32 s98, s98, 0x20000
	s_addc_u32 s99, s99, 0
	global_load_dwordx4 v[236:239], v254, s[98:99] nt
	s_add_u32 s98, s98, 0x20000
	s_addc_u32 s99, s99, 0
	global_load_dwordx4 v[240:243], v254, s[98:99] nt
	s_add_u32 s98, s98, 0x20000
	s_addc_u32 s99, s99, 0
	global_load_dwordx4 v[246:249], v254, s[98:99] nt
.Leng_ld_done:
	s_cmp_eq_u32 s97, 0
	s_cbranch_scc1 .Lengw1_a
	s_cmp_eq_u32 s97, 2
	s_cbranch_scc1 .Lengw1_b
	s_cmp_eq_u32 s97, 4
	s_cbranch_scc1 .Lengw1_c
	s_waitcnt vmcnt(16)
	s_branch .Lengw1_e

; #define PG8_STAGE(bufoff, gbase, voff) do { _Pragma("unroll") for (int _i = 0; _i < 2; ++_i) \
;         __builtin_amdgcn_global_load_lds((const unsigned*)((const char*)(gbase) + (voff)[_i]), (PG8_LAS unsigned*)(lds + (bufoff) + ldsw + _i * 8192), 16, 0, 0); } while (0)
; #define PG8_LDA(dst, b, h) do { _Pragma("unroll") for (int m = 0; m < 4; ++m) _Pragma("unroll") for (int k = 0; k < 2; ++k) dst[m][k] = *(const PG8_LAS bf16x8*)(lds + PG8_SA(b, h) + aoff + m * 2048 + k * 1024); } while (0)
; #define PG8_LDB(dst, b, h) do { _Pragma("unroll") for (int n = 0; n < 2; ++n) _Pragma("unroll") for (int k = 0; k < 2; ++k) dst[n][k] = *(const PG8_LAS bf16x8*)(lds + PG8_SB(b, h) + boff + n * 2048 + k * 1024); } while (0)
; #define PG8_MMA(ai, bj, At, Bt) do { __builtin_amdgcn_s_setprio(3); _Pragma("unroll") for (int m = 0; m < 4; ++m) _Pragma("unroll") for (int n = 0; n < 2; ++n) _Pragma("unroll") for (int k = 0; k < 2; ++k) \
;         acc[ai][bj][m][n] = __builtin_amdgcn_mfma_f32_16x16x32_bf16(Bt[n][k], At[m][k], acc[ai][bj][m][n], 0, 0, 0); __builtin_amdgcn_s_setprio(0); } while (0)
; #define PG8_WAIT_V(n) asm volatile("s_waitcnt vmcnt(" #n ")" ::: "memory")
; #define PG8_WAIT_L(n) asm volatile("s_waitcnt lgkmcnt(" #n ")" ::: "memory")
; #define PG8_BAR __builtin_amdgcn_s_barrier()
; #define PG8_SCHED __builtin_amdgcn_sched_barrier(0)
; template <class Epi, class Sched, bool ALIGN_EPI = false, bool SP2 = false>
; __device__ __forceinline__ void gemm_phase(PG8_LAS unsigned char* lds, const Gemm g, const Sched& S, const Epi& E) {
;     ...
;             PG8_WAIT_V(8); PG8_WAIT_L(0); PG8_BAR; PG8_MMA(1, 0, At, B0); PG8_MMA(1, 1, At, B1); PG8_BAR; PG8_SCHED;
;             PG8_LDB(B0, 1, 0); PG8_LDB(B1, 1, 1); PG8_SCHED; PG8_LDA(At, 1, 0); PG8_STAGE(PG8_SA(0, 1), a2 + hstepA, voffA);
;             PG8_WAIT_V(8); PG8_WAIT_L(0); PG8_BAR; PG8_MMA(0, 0, At, B0); PG8_MMA(0, 1, At, B1); PG8_BAR; PG8_SCHED;
.Lengw2_e:
	s_waitcnt lgkmcnt(0)
	s_barrier
	s_setprio 3
	s_waitcnt lgkmcnt(0)
	v_mfma_f32_16x16x32_bf16 v[62:65], v[130:133], v[192:195], v[62:65]
	v_mfma_f32_16x16x32_bf16 v[54:57], v[156:159], v[192:195], v[54:57]
	v_mfma_f32_16x16x32_bf16 v[46:49], v[130:133], v[200:203], v[46:49]
	v_mfma_f32_16x16x32_bf16 v[38:41], v[156:159], v[200:203], v[38:41]
	v_mfma_f32_16x16x32_bf16 v[30:33], v[130:133], v[208:211], v[30:33]
	v_mfma_f32_16x16x32_bf16 v[22:25], v[156:159], v[208:211], v[22:25]
	v_mfma_f32_16x16x32_bf16 v[14:17], v[130:133], v[216:219], v[14:17]
	v_mfma_f32_16x16x32_bf16 v[6:9], v[156:159], v[216:219], v[6:9]
	v_mfma_f32_16x16x32_bf16 v[62:65], v[134:137], v[196:199], v[62:65]
	v_mfma_f32_16x16x32_bf16 v[54:57], v[172:175], v[196:199], v[54:57]
	v_mfma_f32_16x16x32_bf16 v[46:49], v[134:137], v[204:207], v[46:49]
	v_mfma_f32_16x16x32_bf16 v[38:41], v[172:175], v[204:207], v[38:41]
	v_mfma_f32_16x16x32_bf16 v[30:33], v[134:137], v[212:215], v[30:33]
	v_mfma_f32_16x16x32_bf16 v[22:25], v[172:175], v[212:215], v[22:25]
	v_mfma_f32_16x16x32_bf16 v[14:17], v[134:137], v[220:223], v[14:17]
	v_mfma_f32_16x16x32_bf16 v[6:9], v[172:175], v[220:223], v[6:9]
	s_setprio 0
	s_setprio 3
	v_mfma_f32_16x16x32_bf16 v[58:61], v[176:179], v[192:195], v[58:61]
	v_mfma_f32_16x16x32_bf16 v[50:53], v[184:187], v[192:195], v[50:53]
	v_mfma_f32_16x16x32_bf16 v[42:45], v[176:179], v[200:203], v[42:45]
	v_mfma_f32_16x16x32_bf16 v[34:37], v[184:187], v[200:203], v[34:37]
	v_mfma_f32_16x16x32_bf16 v[26:29], v[176:179], v[208:211], v[26:29]
	v_mfma_f32_16x16x32_bf16 v[18:21], v[184:187], v[208:211], v[18:21]
	v_mfma_f32_16x16x32_bf16 v[10:13], v[176:179], v[216:219], v[10:13]
	v_mfma_f32_16x16x32_bf16 v[2:5], v[184:187], v[216:219], v[2:5]
	v_mfma_f32_16x16x32_bf16 v[58:61], v[180:183], v[196:199], v[58:61]
	v_mfma_f32_16x16x32_bf16 v[50:53], v[188:191], v[196:199], v[50:53]
	v_mfma_f32_16x16x32_bf16 v[42:45], v[180:183], v[204:207], v[42:45]
	v_mfma_f32_16x16x32_bf16 v[34:37], v[188:191], v[204:207], v[34:37]
	v_mfma_f32_16x16x32_bf16 v[26:29], v[180:183], v[212:215], v[26:29]
	v_mfma_f32_16x16x32_bf16 v[18:21], v[188:191], v[212:215], v[18:21]
	v_mfma_f32_16x16x32_bf16 v[10:13], v[180:183], v[220:223], v[10:13]
	v_mfma_f32_16x16x32_bf16 v[2:5], v[188:191], v[220:223], v[2:5]
	s_setprio 0
	s_barrier
	s_add_i32 s56, 0, 0x18000
	v_add_u32_e32 v146, s56, v164
	s_add_i32 s57, 0, 0x1c000
	ds_read_b128 v[130:133], v146
	ds_read_b128 v[134:137], v146 offset:1024
	ds_read_b128 v[156:159], v146 offset:2048
	ds_read_b128 v[172:175], v146 offset:3072
	v_add_u32_e32 v146, s57, v164
	ds_read_b128 v[176:179], v146
	ds_read_b128 v[180:183], v146 offset:1024
	ds_read_b128 v[184:187], v146 offset:2048
	ds_read_b128 v[188:191], v146 offset:3072
	s_add_u32 s36, s36, 0x100000
	s_addc_u32 s37, s37, 0
	s_mov_b32 m0, s72
	v_lshl_add_u64 v[230:231], s[36:37], 0, v[138:139]
	ds_read_b128 v[192:195], v169 offset:32768
	ds_read_b128 v[196:199], v169 offset:33792
	ds_read_b128 v[200:203], v169 offset:34816
	ds_read_b128 v[204:207], v169 offset:35840
	ds_read_b128 v[208:211], v169 offset:36864
	ds_read_b128 v[212:215], v169 offset:37888
	ds_read_b128 v[216:219], v169 offset:38912
	ds_read_b128 v[220:223], v169 offset:39936
	global_load_lds_dwordx4 v[230:231], off
	v_lshl_add_u64 v[230:231], s[36:37], 0, v[142:143]
	s_mov_b32 m0, s73
	s_nop 0
	global_load_lds_dwordx4 v[230:231], off
	s_cmp_eq_u32 s97, 4
	s_cbranch_scc1 .Lengw3_c
	s_cmp_eq_u32 s97, 8
	s_cbranch_scc1 .Lengw3_d
	s_waitcnt vmcnt(8)
	s_branch .Lengw3_e

; #define PG8_STAGE(bufoff, gbase, voff) do { _Pragma("unroll") for (int _i = 0; _i < 2; ++_i) \
;         __builtin_amdgcn_global_load_lds((const unsigned*)((const char*)(gbase) + (voff)[_i]), (PG8_LAS unsigned*)(lds + (bufoff) + ldsw + _i * 8192), 16, 0, 0); } while (0)
; #define PG8_LDA(dst, b, h) do { _Pragma("unroll") for (int m = 0; m < 4; ++m) _Pragma("unroll") for (int k = 0; k < 2; ++k) dst[m][k] = *(const PG8_LAS bf16x8*)(lds + PG8_SA(b, h) + aoff + m * 2048 + k * 1024); } while (0)
; #define PG8_MMA(ai, bj, At, Bt) do { __builtin_amdgcn_s_setprio(3); _Pragma("unroll") for (int m = 0; m < 4; ++m) _Pragma("unroll") for (int n = 0; n < 2; ++n) _Pragma("unroll") for (int k = 0; k < 2; ++k) \
;         acc[ai][bj][m][n] = __builtin_amdgcn_mfma_f32_16x16x32_bf16(Bt[n][k], At[m][k], acc[ai][bj][m][n], 0, 0, 0); __builtin_amdgcn_s_setprio(0); } while (0)
; #define PG8_WAIT_V(n) asm volatile("s_waitcnt vmcnt(" #n ")" ::: "memory")
; #define PG8_WAIT_L(n) asm volatile("s_waitcnt lgkmcnt(" #n ")" ::: "memory")
; #define PG8_BAR __builtin_amdgcn_s_barrier()
; #define PG8_SCHED __builtin_amdgcn_sched_barrier(0)
; template <class Epi, class Sched, bool ALIGN_EPI = false, bool SP2 = false>
; __device__ __forceinline__ void gemm_phase(PG8_LAS unsigned char* lds, const Gemm g, const Sched& S, const Epi& E) {
;     ...
;             PG8_WAIT_V(8); PG8_WAIT_L(0); PG8_BAR; PG8_MMA(0, 0, At, B0); PG8_MMA(0, 1, At, B1); PG8_BAR; PG8_SCHED;
;             PG8_LDA(At, 1, 1); PG8_STAGE(PG8_SB(1, 0), b3, voffB); PG8_STAGE(PG8_SB(1, 1), b3 + hstepB, voffB); PG8_STAGE(PG8_SA(1, 0), a3, voffA);
;             PG8_WAIT_V(8); PG8_WAIT_L(0); PG8_BAR; PG8_MMA(1, 0, At, B0); PG8_MMA(1, 1, At, B1); PG8_BAR; PG8_SCHED;
.Lengw3_d:
	s_waitcnt vmcnt(16)
.Lengw3_e:
	s_waitcnt lgkmcnt(0)
	s_barrier
	s_setprio 3
	s_waitcnt lgkmcnt(0)
	v_mfma_f32_16x16x32_bf16 v[126:129], v[130:133], v[192:195], v[126:129]
	v_mfma_f32_16x16x32_bf16 v[118:121], v[156:159], v[192:195], v[118:121]
	v_mfma_f32_16x16x32_bf16 v[110:113], v[130:133], v[200:203], v[110:113]
	v_mfma_f32_16x16x32_bf16 v[102:105], v[156:159], v[200:203], v[102:105]
	v_mfma_f32_16x16x32_bf16 v[94:97], v[130:133], v[208:211], v[94:97]
	v_mfma_f32_16x16x32_bf16 v[86:89], v[156:159], v[208:211], v[86:89]
	v_mfma_f32_16x16x32_bf16 v[78:81], v[130:133], v[216:219], v[78:81]
	v_mfma_f32_16x16x32_bf16 v[70:73], v[156:159], v[216:219], v[70:73]
	v_mfma_f32_16x16x32_bf16 v[126:129], v[134:137], v[196:199], v[126:129]
	v_mfma_f32_16x16x32_bf16 v[118:121], v[172:175], v[196:199], v[118:121]
	v_mfma_f32_16x16x32_bf16 v[110:113], v[134:137], v[204:207], v[110:113]
	v_mfma_f32_16x16x32_bf16 v[102:105], v[172:175], v[204:207], v[102:105]
	v_mfma_f32_16x16x32_bf16 v[94:97], v[134:137], v[212:215], v[94:97]
	v_mfma_f32_16x16x32_bf16 v[86:89], v[172:175], v[212:215], v[86:89]
	v_mfma_f32_16x16x32_bf16 v[78:81], v[134:137], v[220:223], v[78:81]
	v_mfma_f32_16x16x32_bf16 v[70:73], v[172:175], v[220:223], v[70:73]
	s_setprio 0
	s_setprio 3
	v_mfma_f32_16x16x32_bf16 v[122:125], v[176:179], v[192:195], v[122:125]
	v_mfma_f32_16x16x32_bf16 v[114:117], v[184:187], v[192:195], v[114:117]
	v_mfma_f32_16x16x32_bf16 v[106:109], v[176:179], v[200:203], v[106:109]
	v_mfma_f32_16x16x32_bf16 v[98:101], v[184:187], v[200:203], v[98:101]
	v_mfma_f32_16x16x32_bf16 v[90:93], v[176:179], v[208:211], v[90:93]
	v_mfma_f32_16x16x32_bf16 v[82:85], v[184:187], v[208:211], v[82:85]
	v_mfma_f32_16x16x32_bf16 v[74:77], v[176:179], v[216:219], v[74:77]
	v_mfma_f32_16x16x32_bf16 v[66:69], v[184:187], v[216:219], v[66:69]
	v_mfma_f32_16x16x32_bf16 v[122:125], v[180:183], v[196:199], v[122:125]
	v_mfma_f32_16x16x32_bf16 v[114:117], v[188:191], v[196:199], v[114:117]
	v_mfma_f32_16x16x32_bf16 v[106:109], v[180:183], v[204:207], v[106:109]
	v_mfma_f32_16x16x32_bf16 v[98:101], v[188:191], v[204:207], v[98:101]
	v_mfma_f32_16x16x32_bf16 v[90:93], v[180:183], v[212:215], v[90:93]
	v_mfma_f32_16x16x32_bf16 v[82:85], v[188:191], v[212:215], v[82:85]
	v_mfma_f32_16x16x32_bf16 v[74:77], v[180:183], v[220:223], v[74:77]
	v_mfma_f32_16x16x32_bf16 v[66:69], v[188:191], v[220:223], v[66:69]
	s_setprio 0
	s_barrier
	s_add_i32 s36, s56, s66
	v_lshl_add_u64 v[160:161], v[160:161], 0, s[18:19]
	s_mov_b32 m0, s36
	ds_read_b128 v[192:195], v169 offset:49152
	ds_read_b128 v[196:199], v169 offset:50176
	ds_read_b128 v[200:203], v169 offset:51200
	ds_read_b128 v[204:207], v169 offset:52224
	ds_read_b128 v[208:211], v169 offset:53248
	ds_read_b128 v[212:215], v169 offset:54272
	ds_read_b128 v[216:219], v169 offset:55296
	ds_read_b128 v[220:223], v169 offset:56320
	global_load_lds_dwordx4 v[160:161], off
	s_add_i32 m0, s36, 0x2000
	s_add_u32 s8, s8, 0x100080
	v_lshl_add_u64 v[160:161], v[224:225], 0, s[18:19]
	s_addc_u32 s9, s9, 0
	s_add_i32 s36, s57, s66
	global_load_lds_dwordx4 v[160:161], off
	v_lshl_add_u64 v[160:161], s[8:9], 0, v[140:141]
	s_mov_b32 m0, s36
	s_nop 0
	global_load_lds_dwordx4 v[160:161], off
	v_lshl_add_u64 v[160:161], s[8:9], 0, v[144:145]
	s_add_i32 m0, s36, 0x2000
	s_nop 0
	global_load_lds_dwordx4 v[160:161], off
	v_lshl_add_u64 v[160:161], v[226:227], 0, s[18:19]
	s_mov_b32 m0, s75
	s_nop 0
	global_load_lds_dwordx4 v[160:161], off
	v_lshl_add_u64 v[160:161], v[228:229], 0, s[18:19]
	s_mov_b32 m0, s76
	s_nop 0
	global_load_lds_dwordx4 v[160:161], off
	s_waitcnt vmcnt(8)
	s_waitcnt lgkmcnt(0)
	s_barrier
	s_setprio 3
	s_waitcnt lgkmcnt(0)
	v_mfma_f32_16x16x32_bf16 v[62:65], v[130:133], v[192:195], v[62:65]
	v_mfma_f32_16x16x32_bf16 v[54:57], v[156:159], v[192:195], v[54:57]
	v_mfma_f32_16x16x32_bf16 v[46:49], v[130:133], v[200:203], v[46:49]
	v_mfma_f32_16x16x32_bf16 v[38:41], v[156:159], v[200:203], v[38:41]
	v_mfma_f32_16x16x32_bf16 v[30:33], v[130:133], v[208:211], v[30:33]
	v_mfma_f32_16x16x32_bf16 v[22:25], v[156:159], v[208:211], v[22:25]
	v_mfma_f32_16x16x32_bf16 v[14:17], v[130:133], v[216:219], v[14:17]
	v_mfma_f32_16x16x32_bf16 v[6:9], v[156:159], v[216:219], v[6:9]
	v_mfma_f32_16x16x32_bf16 v[62:65], v[134:137], v[196:199], v[62:65]
	v_mfma_f32_16x16x32_bf16 v[54:57], v[172:175], v[196:199], v[54:57]
	v_mfma_f32_16x16x32_bf16 v[46:49], v[134:137], v[204:207], v[46:49]
	v_mfma_f32_16x16x32_bf16 v[38:41], v[172:175], v[204:207], v[38:41]
	v_mfma_f32_16x16x32_bf16 v[30:33], v[134:137], v[212:215], v[30:33]
	v_mfma_f32_16x16x32_bf16 v[22:25], v[172:175], v[212:215], v[22:25]
	v_mfma_f32_16x16x32_bf16 v[14:17], v[134:137], v[220:223], v[14:17]
	v_mfma_f32_16x16x32_bf16 v[6:9], v[172:175], v[220:223], v[6:9]
	s_setprio 0
	s_setprio 3
	v_mfma_f32_16x16x32_bf16 v[58:61], v[176:179], v[192:195], v[58:61]
	v_mfma_f32_16x16x32_bf16 v[50:53], v[184:187], v[192:195], v[50:53]
	v_mfma_f32_16x16x32_bf16 v[42:45], v[176:179], v[200:203], v[42:45]
	v_mfma_f32_16x16x32_bf16 v[34:37], v[184:187], v[200:203], v[34:37]
	v_mfma_f32_16x16x32_bf16 v[26:29], v[176:179], v[208:211], v[26:29]
	v_mfma_f32_16x16x32_bf16 v[18:21], v[184:187], v[208:211], v[18:21]
	v_mfma_f32_16x16x32_bf16 v[10:13], v[176:179], v[216:219], v[10:13]
	v_mfma_f32_16x16x32_bf16 v[2:5], v[184:187], v[216:219], v[2:5]
	v_mfma_f32_16x16x32_bf16 v[58:61], v[180:183], v[196:199], v[58:61]
	v_mfma_f32_16x16x32_bf16 v[50:53], v[188:191], v[196:199], v[50:53]
	v_mfma_f32_16x16x32_bf16 v[42:45], v[180:183], v[204:207], v[42:45]
	v_mfma_f32_16x16x32_bf16 v[34:37], v[188:191], v[204:207], v[34:37]
	v_mfma_f32_16x16x32_bf16 v[26:29], v[180:183], v[212:215], v[26:29]
	v_mfma_f32_16x16x32_bf16 v[18:21], v[188:191], v[212:215], v[18:21]
	v_mfma_f32_16x16x32_bf16 v[10:13], v[180:183], v[220:223], v[10:13]
	v_mfma_f32_16x16x32_bf16 v[2:5], v[188:191], v[220:223], v[2:5]
	s_setprio 0
	s_barrier
	s_add_i32 s45, s45, 2
	s_add_u32 s6, s6, 0x100
	s_addc_u32 s7, s7, 0
	s_add_u32 s33, s33, 0x100
	s_addc_u32 s44, s44, 0
	s_cmp_gt_u32 s45, 61
	s_cbranch_scc0 .LBB0_143
	s_and_b64 vcc, exec, s[20:21]
	s_cbranch_vccz .LBB0_148
	s_barrier
	v_lshl_add_u32 v156, s0, 8, v163
	s_cmp_lt_i32 s54, 40
	s_mov_b64 s[0:1], -1
	s_cbranch_scc1 .LBB0_149
